# diff loop regenerated the same way: next item's first softmax quarter in the tail gaps, QK chains un-interleaved, even VALU spacing, reads 6 MFMAs ahead
# speedup vs baseline: 1.0443x; 1.0220x over previous
.LBB0_536:
	v_lshl_or_b32 v186, v0, 10, v172
	v_add_u32_e32 v74, 0, v186
	s_waitcnt vmcnt(3)
	s_waitcnt vmcnt(2)
	s_waitcnt vmcnt(1)
	s_waitcnt vmcnt(0)
	ds_read_b128 v[4:7], v74
	ds_read_b128 v[8:11], v74 offset:512
	s_waitcnt lgkmcnt(0)
	v_mfma_f32_32x32x16_bf16 v[76:91], v[8:11], v[50:53], 0
	ds_read_b128 v[8:11], v74 offset:2048
	ds_read_b128 v[12:15], v74 offset:2560
	s_lshl_b32 s2, s42, 8
	s_lshl_b32 s31, s6, 5
	s_add_i32 s4, s31, s2
	s_lshl_b32 s51, s7, 6
	s_lshl_b32 s7, s42, 2
	s_lshl_b32 s3, s10, 13
	s_waitcnt lgkmcnt(0)
	v_mfma_f32_32x32x16_bf16 v[76:91], v[12:15], v[54:57], v[76:91]
	s_ashr_i32 s9, s4, 6
	s_add_i32 s27, s7, 4
	s_add_i32 s52, s3, s2
	v_mfma_f32_32x32x16_bf16 v[92:107], v[4:7], v[50:53], 0
	s_or_b32 s28, s7, 2
	v_mov_b32_e32 v0, v173
	s_cmp_lt_i32 s9, 0
	s_mov_b64 s[2:3], -1
	v_mfma_f32_32x32x16_bf16 v[92:107], v[8:11], v[54:57], v[92:107]
	s_cbranch_scc1 .LBB0_575
	s_cmp_lt_u32 s4, 64
	s_cbranch_scc1 .LBB0_551
	s_lshl_b32 s2, s6, 10
	s_and_b32 s5, s2, 0xc00
	v_mov_b32_e32 v3, 0x3f803f80
	v_cmp_eq_u32_e32 vcc, 0, v2
	s_nop 1
	v_cndmask_b32_e32 v58, 0, v3, vcc
	v_cmp_eq_u32_e32 vcc, 17, v2
	s_nop 1
	v_cndmask_b32_e32 v58, v58, v3, vcc
	v_cmp_eq_u32_e32 vcc, 2, v2
	s_nop 1
	v_cndmask_b32_e32 v62, 0, v3, vcc
	v_cmp_eq_u32_e32 vcc, 19, v2
	s_nop 1
	v_cndmask_b32_e32 v62, v62, v3, vcc
	s_add_i32 s2, s53, s79
	s_ashr_i32 s3, s2, 31
	s_or_b32 s40, s5, 0x1000
	s_or_b32 s41, s5, 0x2000
	s_or_b32 s42, s5, 0x3000
	s_max_u32 s26, s9, 1
	s_lshl_b64 s[2:3], s[2:3], 19
	s_add_u32 s44, s18, s2
	s_addc_u32 s45, s19, s3
	s_add_u32 s46, s18, s34
	v_mov_b32_e32 v59, v58
	v_mov_b32_e32 v60, v58
	v_mov_b32_e32 v61, v58
	v_mov_b32_e32 v63, v62
	v_mov_b32_e32 v64, v62
	v_mov_b32_e32 v65, v62
	s_mov_b32 s43, 1
	s_addc_u32 s47, s19, s35
	v_mov_b32_e32 v108, v0
	v_mov_b32_e32 v109, v0
	v_mov_b32_e32 v110, v0
	v_mov_b32_e32 v111, v0
	v_mov_b32_e32 v112, v0
	v_mov_b32_e32 v113, v0
	v_mov_b32_e32 v114, v0
	v_mov_b32_e32 v115, v0
	v_mov_b32_e32 v116, v0
	v_mov_b32_e32 v117, v0
	v_mov_b32_e32 v118, v0
	v_mov_b32_e32 v119, v0
	v_mov_b32_e32 v120, v0
	v_mov_b32_e32 v121, v0
	v_mov_b32_e32 v122, v0
	v_mov_b32_e32 v123, v0
	v_mov_b32_e32 v124, v0
	v_mov_b32_e32 v125, v0
	v_mov_b32_e32 v126, v0
	v_mov_b32_e32 v127, v0
	v_mov_b32_e32 v128, v0
	v_mov_b32_e32 v129, v0
	v_mov_b32_e32 v130, v0
	v_mov_b32_e32 v131, v0
	v_mov_b32_e32 v132, v0
	v_mov_b32_e32 v133, v0
	v_mov_b32_e32 v134, v0
	v_mov_b32_e32 v135, v0
	v_mov_b32_e32 v136, v0
	v_mov_b32_e32 v137, v0
	v_mov_b32_e32 v138, v0
	v_mov_b32_e32 v139, v0
	v_mov_b32_e32 v140, v0
	v_mov_b32_e32 v141, v0
	v_mov_b32_e32 v142, v0
	v_mov_b32_e32 v143, v0
	v_mov_b32_e32 v144, v0
	v_mov_b32_e32 v145, v0
	v_mov_b32_e32 v146, v0
	v_mov_b32_e32 v147, v0
	v_mov_b32_e32 v148, v0
	v_mov_b32_e32 v149, v0
	v_mov_b32_e32 v150, v0
	v_mov_b32_e32 v151, v0
	v_mov_b32_e32 v152, v0
	v_mov_b32_e32 v153, v0
	v_mov_b32_e32 v154, v0
	v_mov_b32_e32 v155, v0
	v_mov_b32_e32 v2, v0
	v_mov_b32_e32 v3, v0
	v_mov_b32_e32 v4, v0
	v_mov_b32_e32 v5, v0
	v_mov_b32_e32 v6, v0
	v_mov_b32_e32 v7, v0
	v_mov_b32_e32 v8, v0
	v_mov_b32_e32 v9, v0
	v_mov_b32_e32 v10, v0
	v_mov_b32_e32 v11, v0
	v_mov_b32_e32 v12, v0
	v_mov_b32_e32 v13, v0
	v_mov_b32_e32 v14, v0
	v_mov_b32_e32 v15, v0
	v_mov_b32_e32 v16, v0
	v_mov_b32_e32 v17, v0
	v_mov_b32_e32 v156, v0
	v_mov_b32_e32 v157, v0
	v_mov_b32_e32 v158, v0
	v_mov_b32_e32 v159, v0
	v_mov_b32_e32 v160, v0
	v_mov_b32_e32 v161, v0
	v_mov_b32_e32 v162, v0
	v_mov_b32_e32 v163, v0
	v_mov_b32_e32 v164, v0
	v_mov_b32_e32 v165, v0
	v_mov_b32_e32 v166, v0
	v_mov_b32_e32 v167, v0
	v_mov_b32_e32 v168, v0
	v_mov_b32_e32 v169, v0
	v_mov_b32_e32 v170, v0
	v_mov_b32_e32 v171, v0
	v_mov_b32_e32 v75, v74
	ds_read_b128 v[2:5], v75 offset:8192
	ds_read_b128 v[6:9], v75 offset:8704
	ds_read_b128 v[218:221], v75 offset:4096
	ds_read_b128 v[10:13], v75 offset:10240
	ds_read_b128 v[14:17], v75 offset:10752
	v_exp_f32_e32 v92, v92
	v_exp_f32_e32 v93, v93
	v_exp_f32_e32 v94, v94
	v_exp_f32_e32 v95, v95
	v_exp_f32_e32 v96, v96
	v_exp_f32_e32 v97, v97
	v_exp_f32_e32 v98, v98
	v_cvt_pk_bf16_f32 v70, v92, v93
	v_exp_f32_e32 v99, v99
	v_cvt_pk_bf16_f32 v71, v94, v95
	v_cvt_pk_bf16_f32 v72, v96, v97
	v_cvt_pk_bf16_f32 v73, v98, v99
	s_add_i32 s9, s43, -1
	s_cmp_ge_u32 s9, s28
	s_mov_b64 s[2:3], -1
	s_cbranch_scc0 .LBB0_540

.LBB0_547:
	s_and_b32 s2, s9, 3
	s_mulk_i32 s2, 0x5000
	v_add_u32_e32 v75, s2, v74
	s_and_b32 s2, s43, 3
	s_mulk_i32 s2, 0x5000
	v_add_u32_e32 v172, s2, v74
	s_mov_b32 s10, s8
	s_mov_b32 s11, s8
	s_mov_b32 s9, s8
	s_waitcnt lgkmcnt(4)
	v_mfma_f32_32x32x16_bf16 v[156:171], v[2:5], v[70:73], v[156:171]
	v_exp_f32_e32 v100, v100
	v_exp_f32_e32 v101, v101
	v_exp_f32_e32 v102, v102
	s_waitcnt lgkmcnt(3)
	v_mfma_f32_32x32x16_bf16 v[140:155], v[6:9], v[70:73], v[140:155]
	ds_read_b128 v[66:69], v75 offset:6144
	v_exp_f32_e32 v103, v103
	v_exp_f32_e32 v104, v104
	v_exp_f32_e32 v105, v105
	v_mfma_f32_16x16x32_bf16 v[214:217], v[58:61], v[70:73], v[214:217]
	ds_read_b128 v[224:227], v75 offset:12288
	v_exp_f32_e32 v106, v106
	v_cvt_pk_bf16_f32 v182, v100, v101
	s_waitcnt lgkmcnt(4)
	v_mfma_f32_32x32x16_bf16 v[34:49], v[218:221], v[178:181], 0
	ds_read_b128 v[228:231], v75 offset:12800
	v_exp_f32_e32 v107, v107
	v_cvt_pk_bf16_f32 v183, v102, v103
	v_cvt_pk_bf16_f32 v184, v104, v105
	v_cvt_pk_bf16_f32 v185, v106, v107
	s_nop 1
	s_waitcnt lgkmcnt(4)
	v_mfma_f32_32x32x16_bf16 v[156:171], v[10:13], v[182:185], v[156:171]
	v_exp_f32_e32 v76, v76
	v_exp_f32_e32 v77, v77
	v_exp_f32_e32 v78, v78
	s_waitcnt lgkmcnt(3)
	v_mfma_f32_32x32x16_bf16 v[140:155], v[14:17], v[182:185], v[140:155]
	ds_read_b128 v[218:221], v75 offset:4608
	v_exp_f32_e32 v79, v79
	v_exp_f32_e32 v80, v80
	v_exp_f32_e32 v81, v81
	v_mfma_f32_16x16x32_bf16 v[214:217], v[58:61], v[182:185], v[214:217]
	ds_read_b128 v[232:235], v75 offset:14336
	v_exp_f32_e32 v82, v82
	v_cvt_pk_bf16_f32 v70, v76, v77
	s_waitcnt lgkmcnt(4)
	v_mfma_f32_32x32x16_bf16 v[34:49], v[66:69], v[174:177], v[34:49]
	ds_read_b128 v[236:239], v75 offset:14848
	v_exp_f32_e32 v83, v83
	v_cvt_pk_bf16_f32 v71, v78, v79
	v_cvt_pk_bf16_f32 v72, v80, v81
	v_cvt_pk_bf16_f32 v73, v82, v83
	s_nop 1
	s_waitcnt lgkmcnt(4)
	v_mfma_f32_32x32x16_bf16 v[156:171], v[224:227], v[70:73], v[156:171]
	v_exp_f32_e32 v84, v84
	v_exp_f32_e32 v85, v85
	v_exp_f32_e32 v86, v86
	s_waitcnt lgkmcnt(3)
	v_mfma_f32_32x32x16_bf16 v[140:155], v[228:231], v[70:73], v[140:155]
	ds_read_b128 v[66:69], v75 offset:6656
	v_exp_f32_e32 v87, v87
	v_exp_f32_e32 v88, v88
	v_exp_f32_e32 v89, v89
	v_mfma_f32_16x16x32_bf16 v[214:217], v[58:61], v[70:73], v[214:217]
	v_exp_f32_e32 v90, v90
	v_cvt_pk_bf16_f32 v182, v84, v85
	s_waitcnt lgkmcnt(3)
	v_mfma_f32_32x32x16_bf16 v[18:33], v[218:221], v[178:181], 0
	v_exp_f32_e32 v91, v91
	v_cvt_pk_bf16_f32 v183, v86, v87
	v_cvt_pk_bf16_f32 v184, v88, v89
	v_cvt_pk_bf16_f32 v185, v90, v91
	s_nop 1
	s_waitcnt lgkmcnt(2)
	v_mfma_f32_32x32x16_bf16 v[156:171], v[232:235], v[182:185], v[156:171]
	v_exp_f32_e32 v34, v34
	v_exp_f32_e32 v35, v35
	v_exp_f32_e32 v36, v36
	s_waitcnt lgkmcnt(1)
	v_mfma_f32_32x32x16_bf16 v[140:155], v[236:239], v[182:185], v[140:155]
	ds_read_b128 v[218:221], v172
	v_exp_f32_e32 v37, v37
	v_exp_f32_e32 v38, v38
	v_exp_f32_e32 v39, v39
	v_mfma_f32_16x16x32_bf16 v[214:217], v[58:61], v[182:185], v[214:217]
	v_exp_f32_e32 v40, v40
	v_cvt_pk_bf16_f32 v70, v34, v35
	s_waitcnt lgkmcnt(1)
	v_mfma_f32_32x32x16_bf16 v[18:33], v[66:69], v[174:177], v[18:33]
	v_exp_f32_e32 v41, v41
	v_cvt_pk_bf16_f32 v71, v36, v37
	v_cvt_pk_bf16_f32 v72, v38, v39
	v_cvt_pk_bf16_f32 v73, v40, v41
	s_nop 1
	s_cmp_lg_u32 s43, s26
	s_cbranch_scc0 .Ldiff_b_last
	v_mfma_f32_32x32x16_bf16 v[124:139], v[2:5], v[70:73], v[124:139]
	v_exp_f32_e32 v42, v42
	v_exp_f32_e32 v43, v43
	v_exp_f32_e32 v44, v44
	v_mfma_f32_32x32x16_bf16 v[108:123], v[6:9], v[70:73], v[108:123]
	ds_read_b128 v[66:69], v172 offset:2048
	v_exp_f32_e32 v45, v45
	v_exp_f32_e32 v46, v46
	v_exp_f32_e32 v47, v47
	v_mfma_f32_16x16x32_bf16 v[214:217], v[62:65], v[70:73], v[214:217]
	v_exp_f32_e32 v48, v48
	v_cvt_pk_bf16_f32 v182, v42, v43
	s_waitcnt lgkmcnt(1)
	v_mfma_f32_32x32x16_bf16 v[92:107], v[218:221], v[50:53], 0
	v_exp_f32_e32 v49, v49
	v_cvt_pk_bf16_f32 v183, v44, v45
	v_cvt_pk_bf16_f32 v184, v46, v47
	v_cvt_pk_bf16_f32 v185, v48, v49
	s_nop 1
	v_mfma_f32_32x32x16_bf16 v[124:139], v[10:13], v[182:185], v[124:139]
	v_exp_f32_e32 v18, v18
	v_exp_f32_e32 v19, v19
	v_exp_f32_e32 v20, v20
	v_mfma_f32_32x32x16_bf16 v[108:123], v[14:17], v[182:185], v[108:123]
	ds_read_b128 v[218:221], v172 offset:512
	v_exp_f32_e32 v21, v21
	v_exp_f32_e32 v22, v22
	v_exp_f32_e32 v23, v23
	v_mfma_f32_16x16x32_bf16 v[214:217], v[62:65], v[182:185], v[214:217]
	v_exp_f32_e32 v24, v24
	v_cvt_pk_bf16_f32 v70, v18, v19
	s_waitcnt lgkmcnt(1)
	v_mfma_f32_32x32x16_bf16 v[92:107], v[66:69], v[54:57], v[92:107]
	v_exp_f32_e32 v25, v25
	v_cvt_pk_bf16_f32 v71, v20, v21
	v_cvt_pk_bf16_f32 v72, v22, v23
	v_cvt_pk_bf16_f32 v73, v24, v25
	s_nop 1
	v_mfma_f32_32x32x16_bf16 v[124:139], v[224:227], v[70:73], v[124:139]
	v_exp_f32_e32 v26, v26
	v_exp_f32_e32 v27, v27
	v_exp_f32_e32 v28, v28
	v_mfma_f32_32x32x16_bf16 v[108:123], v[228:231], v[70:73], v[108:123]
	ds_read_b128 v[66:69], v172 offset:2560
	v_exp_f32_e32 v29, v29
	v_exp_f32_e32 v30, v30
	v_exp_f32_e32 v31, v31
	v_mfma_f32_16x16x32_bf16 v[214:217], v[62:65], v[70:73], v[214:217]
	ds_read_b128 v[2:5], v172 offset:8192
	v_exp_f32_e32 v32, v32
	v_cvt_pk_bf16_f32 v182, v26, v27
	s_waitcnt lgkmcnt(2)
	v_mfma_f32_32x32x16_bf16 v[76:91], v[218:221], v[50:53], 0
	ds_read_b128 v[6:9], v172 offset:8704
	v_exp_f32_e32 v33, v33
	v_cvt_pk_bf16_f32 v183, v28, v29
	v_cvt_pk_bf16_f32 v184, v30, v31
	v_cvt_pk_bf16_f32 v185, v32, v33
	s_nop 1
	v_mfma_f32_32x32x16_bf16 v[124:139], v[232:235], v[182:185], v[124:139]
	v_exp_f32_e32 v92, v92
	v_exp_f32_e32 v93, v93
	v_exp_f32_e32 v94, v94
	v_mfma_f32_32x32x16_bf16 v[108:123], v[236:239], v[182:185], v[108:123]
	ds_read_b128 v[218:221], v172 offset:4096
	v_exp_f32_e32 v95, v95
	v_exp_f32_e32 v96, v96
	v_exp_f32_e32 v97, v97
	v_mfma_f32_16x16x32_bf16 v[214:217], v[62:65], v[182:185], v[214:217]
	ds_read_b128 v[10:13], v172 offset:10240
	v_exp_f32_e32 v98, v98
	v_cvt_pk_bf16_f32 v70, v92, v93
	s_waitcnt lgkmcnt(4)
	v_mfma_f32_32x32x16_bf16 v[76:91], v[66:69], v[54:57], v[76:91]
	ds_read_b128 v[14:17], v172 offset:10752
	v_exp_f32_e32 v99, v99
	v_cvt_pk_bf16_f32 v71, v94, v95
	v_cvt_pk_bf16_f32 v72, v96, v97
	v_cvt_pk_bf16_f32 v73, v98, v99
	s_nop 1
	s_add_i32 s2, s43, 1
	s_add_u32 s44, s44, 0x1000
	s_addc_u32 s45, s45, 0
	s_add_u32 s46, s46, 0x2000
	s_addc_u32 s47, s47, 0
	s_mov_b32 s43, s2
	s_add_i32 s9, s43, -1
	s_cmp_ge_u32 s9, s28
	s_mov_b64 s[2:3], -1
	s_cbranch_scc1 .LBB0_539
	s_branch .LBB0_540
.Ldiff_b_last:
	v_mfma_f32_32x32x16_bf16 v[124:139], v[2:5], v[70:73], v[124:139]
	v_exp_f32_e32 v42, v42
	v_exp_f32_e32 v43, v43
	v_exp_f32_e32 v44, v44
	v_mfma_f32_32x32x16_bf16 v[108:123], v[6:9], v[70:73], v[108:123]
	ds_read_b128 v[66:69], v172 offset:2048
	v_exp_f32_e32 v45, v45
	v_exp_f32_e32 v46, v46
	v_exp_f32_e32 v47, v47
	v_mfma_f32_16x16x32_bf16 v[214:217], v[62:65], v[70:73], v[214:217]
	v_exp_f32_e32 v48, v48
	v_cvt_pk_bf16_f32 v182, v42, v43
	s_waitcnt lgkmcnt(1)
	v_mfma_f32_32x32x16_bf16 v[92:107], v[218:221], v[50:53], 0
	v_exp_f32_e32 v49, v49
	v_cvt_pk_bf16_f32 v183, v44, v45
	v_cvt_pk_bf16_f32 v184, v46, v47
	v_cvt_pk_bf16_f32 v185, v48, v49
	s_nop 1
	v_mfma_f32_32x32x16_bf16 v[124:139], v[10:13], v[182:185], v[124:139]
	v_exp_f32_e32 v18, v18
	v_exp_f32_e32 v19, v19
	v_exp_f32_e32 v20, v20
	v_mfma_f32_32x32x16_bf16 v[108:123], v[14:17], v[182:185], v[108:123]
	ds_read_b128 v[218:221], v172 offset:512
	v_exp_f32_e32 v21, v21
	v_exp_f32_e32 v22, v22
	v_exp_f32_e32 v23, v23
	v_mfma_f32_16x16x32_bf16 v[214:217], v[62:65], v[182:185], v[214:217]
	v_exp_f32_e32 v24, v24
	v_cvt_pk_bf16_f32 v70, v18, v19
	s_waitcnt lgkmcnt(1)
	v_mfma_f32_32x32x16_bf16 v[92:107], v[66:69], v[54:57], v[92:107]
	v_exp_f32_e32 v25, v25
	v_cvt_pk_bf16_f32 v71, v20, v21
	v_cvt_pk_bf16_f32 v72, v22, v23
	v_cvt_pk_bf16_f32 v73, v24, v25
	s_nop 1
	v_mfma_f32_32x32x16_bf16 v[124:139], v[224:227], v[70:73], v[124:139]
	v_exp_f32_e32 v26, v26
	v_exp_f32_e32 v27, v27
	v_exp_f32_e32 v28, v28
	v_mfma_f32_32x32x16_bf16 v[108:123], v[228:231], v[70:73], v[108:123]
	ds_read_b128 v[66:69], v172 offset:2560
	v_exp_f32_e32 v29, v29
	v_exp_f32_e32 v30, v30
	v_exp_f32_e32 v31, v31
	v_mfma_f32_16x16x32_bf16 v[214:217], v[62:65], v[70:73], v[214:217]
	v_exp_f32_e32 v32, v32
	v_cvt_pk_bf16_f32 v182, v26, v27
	s_waitcnt lgkmcnt(1)
	v_mfma_f32_32x32x16_bf16 v[76:91], v[218:221], v[50:53], 0
	v_exp_f32_e32 v33, v33
	v_cvt_pk_bf16_f32 v183, v28, v29
	v_cvt_pk_bf16_f32 v184, v30, v31
	v_cvt_pk_bf16_f32 v185, v32, v33
	s_nop 1
	v_mfma_f32_32x32x16_bf16 v[124:139], v[232:235], v[182:185], v[124:139]
	v_mfma_f32_32x32x16_bf16 v[108:123], v[236:239], v[182:185], v[108:123]
	v_mfma_f32_16x16x32_bf16 v[214:217], v[62:65], v[182:185], v[214:217]
	s_waitcnt lgkmcnt(0)
	v_mfma_f32_32x32x16_bf16 v[76:91], v[66:69], v[54:57], v[76:91]
	s_add_i32 s2, s43, 1
	s_add_u32 s44, s44, 0x1000
	s_addc_u32 s45, s45, 0
	s_add_u32 s46, s46, 0x2000
	s_addc_u32 s47, s47, 0
	s_branch .LBB0_552
